# adaLN norm loops: next-row prefetch no longer drained by the vmcnt ladder (counted waits); plus MFMA accumulate-chain issue order
# speedup vs baseline: 1.6220x; 1.0074x over previous
.LBB0_178:
	s_or_b64 exec, exec, s[6:7]
	s_abs_i32 s8, s22
	s_waitcnt lgkmcnt(0)
	v_cvt_f32_u32_e32 v1, s8
	s_sub_i32 s11, 0, s8
	s_add_i32 s9, s22, 0x4fff
	s_xor_b32 s10, s9, s22
	v_rcp_iflag_f32_e32 v1, v1
	s_abs_i32 s9, s9
	s_ashr_i32 s10, s10, 31
	s_mov_b64 s[6:7], s[0:1]
	v_mul_f32_e32 v1, 0x4f7ffffe, v1
	v_cvt_u32_f32_e32 v1, v1
	v_mov_b32_e32 v131, 0
	v_or_b32_e32 v199, 0x200, v200
	v_or_b32_e32 v219, 0x300, v200
	v_readfirstlane_b32 s12, v1
	s_mul_i32 s11, s11, s12
	s_mul_hi_u32 s11, s12, s11
	s_add_i32 s12, s12, s11
	s_mul_hi_u32 s11, s9, s12
	s_mul_i32 s12, s11, s8
	s_sub_i32 s9, s9, s12
	s_add_i32 s12, s11, 1
	s_sub_i32 s13, s9, s8
	s_cmp_ge_u32 s9, s8
	s_cselect_b32 s11, s12, s11
	s_cselect_b32 s9, s13, s9
	s_add_i32 s12, s11, 1
	s_cmp_ge_u32 s9, s8
	s_cselect_b32 s8, s12, s11
	s_xor_b32 s8, s8, s10
	s_sub_i32 s8, s8, s10
	s_mul_i32 s46, s8, s20
	s_add_i32 s8, s46, s8
	s_min_i32 s73, s8, 0x5000
	s_cmp_lt_i32 s46, s73
	s_cselect_b64 s[48:49], -1, 0
	v_or_b32_e32 v1, 0x100, v200
	v_or_b32_e32 v220, 0x400, v200
	v_or_b32_e32 v221, 0x500, v200
	v_or_b32_e32 v222, 0x600, v200
	v_or_b32_e32 v223, 0x700, v200
	s_and_b64 vcc, exec, s[48:49]
	v_mbcnt_lo_u32_b32 v224, -1, 0
	s_barrier
	s_cbranch_vccz .LBB0_189
	s_load_dwordx2 s[14:15], s[6:7], 0x110
	s_load_dwordx4 s[8:11], s[6:7], 0x0
	v_lshlrev_b32_e32 v130, 2, v200
	s_movk_i32 s12, 0x1000
	v_mbcnt_hi_u32_b32 v136, -1, v224
	s_waitcnt lgkmcnt(0)
	s_add_u32 s20, s14, 0x180000
	s_addc_u32 s21, s15, 0
	s_ashr_i32 s47, s46, 31
	s_add_i32 s6, s46, 0xfffff000
	s_cmpk_lt_i32 s46, 0x1000
	s_cselect_b32 s7, s47, 0
	s_cselect_b32 s6, s46, s6
	s_cselect_b32 s13, s9, s11
	s_cselect_b32 s16, s8, s10
	s_lshl_b64 s[6:7], s[6:7], 13
	s_add_u32 s6, s16, s6
	s_addc_u32 s7, s13, s7
	v_lshl_add_u64 v[2:3], s[6:7], 0, v[130:131]
	global_load_dwordx4 v[126:129], v130, s[6:7] nt
	global_load_dwordx4 v[122:125], v130, s[6:7] offset:1024 nt
	v_add_co_u32_e32 v6, vcc, s12, v2
	v_and_b32_e32 v137, 64, v136
	s_nop 0
	v_addc_co_u32_e32 v7, vcc, 0, v3, vcc
	global_load_dwordx4 v[2:5], v[6:7], off offset:2048 nt
	global_load_dwordx4 v[114:117], v[6:7], off offset:3072 nt
	global_load_dwordx4 v[118:121], v130, s[6:7] offset:2048 nt
	global_load_dwordx4 v[110:113], v130, s[6:7] offset:3072 nt
	global_load_dwordx4 v[106:109], v[6:7], off nt
	global_load_dwordx4 v[62:65], v[6:7], off offset:1024 nt
	v_xor_b32_e32 v138, 1, v136
	v_add_u32_e32 v137, 64, v137
	v_xor_b32_e32 v139, 2, v136
	v_cmp_lt_i32_e32 vcc, v138, v137
	v_xor_b32_e32 v140, 4, v136
	v_xor_b32_e32 v141, 8, v136
	v_cndmask_b32_e32 v138, v136, v138, vcc
	v_cmp_lt_i32_e32 vcc, v139, v137
	v_xor_b32_e32 v142, 16, v136
	s_lshl_b64 s[18:19], s[46:47], 12
	v_cndmask_b32_e32 v139, v136, v139, vcc
	v_cmp_lt_i32_e32 vcc, v140, v137
	v_xor_b32_e32 v143, 32, v136
	s_add_u32 s14, s14, s18
	v_cndmask_b32_e32 v140, v136, v140, vcc
	v_cmp_lt_i32_e32 vcc, v141, v137
	v_lshlrev_b32_e32 v132, 3, v198
	v_mov_b32_e32 v133, v131
	v_cndmask_b32_e32 v141, v136, v141, vcc
	v_cmp_lt_i32_e32 vcc, v142, v137
	s_addc_u32 s15, s15, s19
	s_mov_b64 s[16:17], 0x9100000
	v_cndmask_b32_e32 v142, v136, v142, vcc
	v_cmp_lt_i32_e32 vcc, v143, v137
	v_lshl_add_u64 v[132:133], s[14:15], 0, v[132:133]
	s_mov_b32 s22, -1
	v_cndmask_b32_e32 v143, v136, v143, vcc
	v_mov_b32_e32 v134, 0x358637bd
	s_mov_b32 s23, 0xf800000
	v_mov_b32_e32 v135, 0x260
	s_movk_i32 s24, 0x7fff
	s_mov_b32 s25, 0xffff0000
	s_mov_b64 s[12:13], 0x1000
	v_lshlrev_b32_e32 v136, 2, v138
	v_lshlrev_b32_e32 v137, 2, v139
	v_lshlrev_b32_e32 v138, 2, v140
	v_lshlrev_b32_e32 v139, 2, v141
	v_lshlrev_b32_e32 v140, 2, v142
	v_lshlrev_b32_e32 v141, 2, v143
	s_mov_b64 s[6:7], s[46:47]
	v_lshl_add_u64 v[132:133], v[132:133], 0, s[16:17]
	s_waitcnt vmcnt(0)
	v_mov_b32_e32 v145, v114
	v_mov_b32_e32 v144, v115
	v_mov_b32_e32 v143, v116
	v_mov_b32_e32 v142, v117
	s_branch .LBB0_181

.LBB0_185:
	s_add_i32 s7, s6, 0xfffff000
	s_ashr_i32 s7, s7, 12
	s_add_i32 s7, s7, 1
	s_cmpk_gt_i32 s6, 0xfff
	s_cselect_b32 s6, s7, 0
	s_cmp_eq_u32 s6, s22
	s_cbranch_scc1 .LBB0_187
	s_ashr_i32 s7, s6, 31
	s_lshl_b64 s[18:19], s[6:7], 14
	s_add_u32 s18, s20, s18
	s_addc_u32 s19, s21, s19
	s_add_u32 s26, s18, 0x2000
	s_addc_u32 s27, s19, 0
	v_lshlrev_b32_e32 v50, 2, v1
	v_lshlrev_b32_e32 v51, 2, v199
	v_lshlrev_b32_e32 v66, 2, v219
	v_lshlrev_b32_e32 v67, 2, v220
	v_lshlrev_b32_e32 v74, 2, v221
	v_lshlrev_b32_e32 v82, 2, v222
	v_lshlrev_b32_e32 v102, 2, v223
	global_load_dwordx4 v[38:41], v130, s[18:19] offset:1024
	global_load_dwordx4 v[42:45], v130, s[18:19] offset:2048
	global_load_dwordx4 v[58:61], v50, s[26:27]
	global_load_dwordx4 v[54:57], v51, s[26:27]
	global_load_dwordx4 v[70:73], v130, s[26:27]
	global_load_dwordx4 v[46:49], v130, s[18:19] offset:3072
	global_load_dwordx4 v[78:81], v66, s[26:27]
	s_nop 0
	global_load_dwordx4 v[50:53], v67, s[18:19]
	global_load_dwordx4 v[86:89], v67, s[26:27]
	s_nop 0
	global_load_dwordx4 v[66:69], v74, s[18:19]
	global_load_dwordx4 v[90:93], v74, s[26:27]
	s_nop 0
	global_load_dwordx4 v[74:77], v82, s[18:19]
	global_load_dwordx4 v[98:101], v82, s[26:27]
	s_nop 0
	global_load_dwordx4 v[82:85], v102, s[18:19]
	global_load_dwordx4 v[94:97], v130, s[18:19]
	s_nop 0
	global_load_dwordx4 v[102:105], v102, s[26:27]
	s_waitcnt vmcnt(0)
	s_mov_b32 s22, s6
.LBB0_187:
	v_pk_mul_f32 v[158:159], v[126:127], v[126:127]
	v_pk_mul_f32 v[160:161], v[122:123], v[122:123]
	v_pk_mul_f32 v[154:155], v[128:129], v[128:129]
	v_pk_mul_f32 v[156:157], v[124:125], v[124:125]
	v_mov_b32_e32 v162, v158
	v_mov_b32_e32 v163, v160
	v_mov_b32_e32 v160, v159
	v_pk_mul_f32 v[150:151], v[120:121], v[120:121]
	v_pk_mul_f32 v[152:153], v[118:119], v[118:119]
	v_pk_add_f32 v[158:159], v[162:163], v[160:161]
	v_mov_b32_e32 v160, v154
	v_mov_b32_e32 v161, v156
	v_mov_b32_e32 v156, v155
	v_pk_add_f32 v[154:155], v[160:161], v[156:157]
	v_pk_mov_b32 v[156:157], v[152:153], v[150:151] op_sel:[1,0]
	v_mov_b32_e32 v153, v151
	v_pk_add_f32 v[150:151], v[156:157], v[152:153]
	v_pk_add_f32 v[154:155], v[158:159], v[154:155]
	v_pk_add_f32 v[150:151], v[150:151], v[150:151] op_sel_hi:[0,1]
	v_mul_f32_e32 v150, v110, v110
	v_pk_fma_f32 v[152:153], v[110:111], v[110:111], v[150:151] op_sel_hi:[1,1,0]
	v_mul_f32_e32 v150, v112, v112
	v_pk_add_f32 v[154:155], v[154:155], v[154:155] op_sel_hi:[0,1]
	v_pk_fma_f32 v[156:157], v[112:113], v[112:113], v[150:151] op_sel_hi:[1,1,0]
	v_mul_f32_e32 v152, v106, v106
	v_mul_f32_e32 v156, v107, v107
	v_mul_f32_e32 v150, v108, v108
	v_mul_f32_e32 v154, v109, v109
	v_pk_mul_f32 v[146:147], v[64:65], v[64:65]
	v_pk_mul_f32 v[148:149], v[62:63], v[62:63]
	v_pk_add_f32 v[152:153], v[152:153], v[156:157]
	v_pk_add_f32 v[150:151], v[150:151], v[154:155]
	s_nop 0
	v_pk_add_f32 v[150:151], v[152:153], v[150:151]
	v_pk_mov_b32 v[152:153], v[148:149], v[146:147] op_sel:[1,0]
	v_mov_b32_e32 v149, v147
	v_pk_add_f32 v[146:147], v[152:153], v[148:149]
	v_pk_add_f32 v[150:151], v[150:151], v[150:151] op_sel_hi:[0,1]
	v_pk_add_f32 v[146:147], v[146:147], v[146:147] op_sel_hi:[0,1]
	v_mul_f32_e32 v146, v2, v2
	v_pk_fma_f32 v[148:149], v[2:3], v[2:3], v[146:147] op_sel_hi:[1,1,0]
	v_mul_f32_e32 v146, v4, v4
	v_pk_fma_f32 v[152:153], v[4:5], v[4:5], v[146:147] op_sel_hi:[1,1,0]
	v_mul_f32_e32 v148, v145, v145
	v_mul_f32_e32 v152, v144, v144
	v_mul_f32_e32 v146, v143, v143
	v_mul_f32_e32 v150, v142, v142
	v_pk_add_f32 v[142:143], v[148:149], v[152:153]
	v_pk_add_f32 v[144:145], v[146:147], v[150:151]
	s_nop 0
	v_pk_add_f32 v[142:143], v[142:143], v[144:145]
	s_nop 0
	v_add_f32_e32 v142, v142, v143
	ds_bpermute_b32 v143, v136, v142
	s_waitcnt lgkmcnt(0)
	v_add_f32_e32 v142, v142, v143
	ds_bpermute_b32 v143, v137, v142
	s_waitcnt lgkmcnt(0)
	v_add_f32_e32 v142, v142, v143
	ds_bpermute_b32 v143, v138, v142
	s_waitcnt lgkmcnt(0)
	v_add_f32_e32 v142, v142, v143
	ds_bpermute_b32 v143, v139, v142
	s_waitcnt lgkmcnt(0)
	v_add_f32_e32 v142, v142, v143
	ds_bpermute_b32 v143, v140, v142
	s_waitcnt lgkmcnt(0)
	v_add_f32_e32 v142, v142, v143
	ds_bpermute_b32 v143, v141, v142
	s_waitcnt lgkmcnt(0)
	v_add_f32_e32 v142, v142, v143
	v_fmamk_f32 v142, v142, 0x3a000000, v134
	v_mul_f32_e32 v143, 0x4f800000, v142
	v_cmp_gt_f32_e32 vcc, s23, v142
	s_nop 1
	v_cndmask_b32_e32 v142, v142, v143, vcc
	v_sqrt_f32_e32 v143, v142
	s_nop 0
	v_add_u32_e32 v144, -1, v143
	v_fma_f32 v145, -v144, v143, v142
	v_cmp_ge_f32_e64 s[6:7], 0, v145
	v_add_u32_e32 v145, 1, v143
	s_nop 0
	v_cndmask_b32_e64 v144, v143, v144, s[6:7]
	v_fma_f32 v143, -v145, v143, v142
	v_cmp_lt_f32_e64 s[6:7], 0, v143
	s_nop 1
	v_cndmask_b32_e64 v143, v144, v145, s[6:7]
	v_mul_f32_e32 v144, 0x37800000, v143
	v_cndmask_b32_e32 v143, v143, v144, vcc
	v_cmp_class_f32_e32 vcc, v142, v135
	s_nop 1
	v_cndmask_b32_e32 v142, v143, v142, vcc
	v_div_scale_f32 v143, s[6:7], v142, v142, 1.0
	v_rcp_f32_e32 v144, v143
	s_mov_b64 s[6:7], -1
	v_fma_f32 v145, -v143, v144, 1.0
	v_fmac_f32_e32 v144, v145, v144
	v_div_scale_f32 v145, vcc, 1.0, v142, 1.0
	v_mul_f32_e32 v146, v145, v144
	v_fma_f32 v147, -v143, v146, v145
	v_fmac_f32_e32 v146, v147, v144
	v_fma_f32 v143, -v143, v146, v145
	v_div_fmas_f32 v143, v143, v144, v146
	v_div_fixup_f32 v142, v143, v142, 1.0
	v_pk_mul_f32 v[126:127], v[126:127], v[142:143] op_sel_hi:[1,0]
	v_pk_mul_f32 v[128:129], v[128:129], v[142:143] op_sel_hi:[1,0]
	v_pk_fma_f32 v[126:127], v[94:95], v[126:127], v[70:71]
	v_pk_fma_f32 v[128:129], v[96:97], v[128:129], v[72:73]
	v_bfe_u32 v143, v126, 16, 1
	v_add3_u32 v126, v126, v143, s24
	v_bfe_u32 v143, v127, 16, 1
	v_lshrrev_b32_e32 v126, 16, v126
	v_add3_u32 v127, v127, v143, s24
	v_and_or_b32 v126, v127, s25, v126
	v_bfe_u32 v127, v128, 16, 1
	v_add3_u32 v127, v128, v127, s24
	v_bfe_u32 v128, v129, 16, 1
	v_lshrrev_b32_e32 v127, 16, v127
	v_add3_u32 v128, v129, v128, s24
	v_pk_mul_f32 v[122:123], v[122:123], v[142:143] op_sel_hi:[1,0]
	v_and_or_b32 v127, v128, s25, v127
	v_pk_fma_f32 v[122:123], v[38:39], v[122:123], v[58:59]
	global_store_dwordx2 v[132:133], v[126:127], off
	v_bfe_u32 v126, v122, 16, 1
	v_pk_mul_f32 v[124:125], v[124:125], v[142:143] op_sel_hi:[1,0]
	v_add3_u32 v122, v122, v126, s24
	v_bfe_u32 v126, v123, 16, 1
	v_pk_fma_f32 v[124:125], v[40:41], v[124:125], v[60:61]
	v_lshrrev_b32_e32 v122, 16, v122
	v_add3_u32 v123, v123, v126, s24
	v_and_or_b32 v122, v123, s25, v122
	v_bfe_u32 v123, v124, 16, 1
	v_add3_u32 v123, v124, v123, s24
	v_bfe_u32 v124, v125, 16, 1
	v_lshrrev_b32_e32 v123, 16, v123
	v_add3_u32 v124, v125, v124, s24
	v_pk_mul_f32 v[118:119], v[118:119], v[142:143] op_sel_hi:[1,0]
	v_and_or_b32 v123, v124, s25, v123
	v_pk_fma_f32 v[118:119], v[42:43], v[118:119], v[54:55]
	global_store_dwordx2 v[132:133], v[122:123], off offset:512
	v_bfe_u32 v122, v118, 16, 1
	v_pk_mul_f32 v[120:121], v[120:121], v[142:143] op_sel_hi:[1,0]
	v_add3_u32 v118, v118, v122, s24
	v_bfe_u32 v122, v119, 16, 1
	v_pk_fma_f32 v[120:121], v[44:45], v[120:121], v[56:57]
	v_lshrrev_b32_e32 v118, 16, v118
	v_add3_u32 v119, v119, v122, s24
	v_and_or_b32 v118, v119, s25, v118
	v_bfe_u32 v119, v120, 16, 1
	v_add3_u32 v119, v120, v119, s24
	v_bfe_u32 v120, v121, 16, 1
	v_lshrrev_b32_e32 v119, 16, v119
	v_add3_u32 v120, v121, v120, s24
	v_pk_mul_f32 v[110:111], v[110:111], v[142:143] op_sel_hi:[1,0]
	v_and_or_b32 v119, v120, s25, v119
	v_pk_fma_f32 v[110:111], v[46:47], v[110:111], v[78:79]
	global_store_dwordx2 v[132:133], v[118:119], off offset:1024
	v_bfe_u32 v118, v110, 16, 1
	v_pk_mul_f32 v[112:113], v[112:113], v[142:143] op_sel_hi:[1,0]
	v_add3_u32 v110, v110, v118, s24
	v_bfe_u32 v118, v111, 16, 1
	v_pk_fma_f32 v[112:113], v[48:49], v[112:113], v[80:81]
	v_lshrrev_b32_e32 v110, 16, v110
	v_add3_u32 v111, v111, v118, s24
	v_and_or_b32 v110, v111, s25, v110
	v_bfe_u32 v111, v112, 16, 1
	v_add3_u32 v111, v112, v111, s24
	v_bfe_u32 v112, v113, 16, 1
	v_lshrrev_b32_e32 v111, 16, v111
	v_add3_u32 v112, v113, v112, s24
	v_pk_mul_f32 v[106:107], v[106:107], v[142:143] op_sel_hi:[1,0]
	v_and_or_b32 v111, v112, s25, v111
	v_pk_fma_f32 v[106:107], v[50:51], v[106:107], v[86:87]
	global_store_dwordx2 v[132:133], v[110:111], off offset:1536
	v_bfe_u32 v110, v106, 16, 1
	v_pk_mul_f32 v[108:109], v[108:109], v[142:143] op_sel_hi:[1,0]
	v_add3_u32 v106, v106, v110, s24
	v_bfe_u32 v110, v107, 16, 1
	v_pk_fma_f32 v[108:109], v[52:53], v[108:109], v[88:89]
	v_lshrrev_b32_e32 v106, 16, v106
	v_add3_u32 v107, v107, v110, s24
	v_and_or_b32 v106, v107, s25, v106
	v_bfe_u32 v107, v108, 16, 1
	v_add3_u32 v107, v108, v107, s24
	v_bfe_u32 v108, v109, 16, 1
	v_lshrrev_b32_e32 v107, 16, v107
	v_add3_u32 v108, v109, v108, s24
	v_pk_mul_f32 v[62:63], v[62:63], v[142:143] op_sel_hi:[1,0]
	v_and_or_b32 v107, v108, s25, v107
	v_pk_fma_f32 v[62:63], v[66:67], v[62:63], v[90:91]
	global_store_dwordx2 v[132:133], v[106:107], off offset:2048
	v_bfe_u32 v106, v62, 16, 1
	v_pk_mul_f32 v[64:65], v[64:65], v[142:143] op_sel_hi:[1,0]
	v_add3_u32 v62, v62, v106, s24
	v_bfe_u32 v106, v63, 16, 1
	v_pk_fma_f32 v[64:65], v[68:69], v[64:65], v[92:93]
	v_lshrrev_b32_e32 v62, 16, v62
	v_add3_u32 v63, v63, v106, s24
	v_and_or_b32 v62, v63, s25, v62
	v_bfe_u32 v63, v64, 16, 1
	v_add3_u32 v63, v64, v63, s24
	v_bfe_u32 v64, v65, 16, 1
	v_lshrrev_b32_e32 v63, 16, v63
	v_add3_u32 v64, v65, v64, s24
	v_pk_mul_f32 v[2:3], v[2:3], v[142:143] op_sel_hi:[1,0]
	v_and_or_b32 v63, v64, s25, v63
	v_pk_fma_f32 v[2:3], v[74:75], v[2:3], v[98:99]
	global_store_dwordx2 v[132:133], v[62:63], off offset:2560
	v_bfe_u32 v62, v2, 16, 1
	v_pk_mul_f32 v[4:5], v[4:5], v[142:143] op_sel_hi:[1,0]
	v_add3_u32 v2, v2, v62, s24
	v_bfe_u32 v62, v3, 16, 1
	v_pk_fma_f32 v[4:5], v[76:77], v[4:5], v[100:101]
	v_lshrrev_b32_e32 v2, 16, v2
	v_add3_u32 v3, v3, v62, s24
	v_and_or_b32 v2, v3, s25, v2
	v_bfe_u32 v3, v4, 16, 1
	v_add3_u32 v3, v4, v3, s24
	v_bfe_u32 v4, v5, 16, 1
	v_lshrrev_b32_e32 v3, 16, v3
	v_add3_u32 v4, v5, v4, s24
	v_and_or_b32 v3, v4, s25, v3
	global_store_dwordx2 v[132:133], v[2:3], off offset:3072
	v_pk_mul_f32 v[2:3], v[114:115], v[142:143] op_sel_hi:[1,0]
	v_pk_mul_f32 v[4:5], v[116:117], v[142:143] op_sel_hi:[1,0]
	v_pk_fma_f32 v[2:3], v[82:83], v[2:3], v[102:103]
	v_pk_fma_f32 v[4:5], v[84:85], v[4:5], v[104:105]
	v_bfe_u32 v62, v2, 16, 1
	v_add3_u32 v2, v2, v62, s24
	v_bfe_u32 v62, v3, 16, 1
	v_lshrrev_b32_e32 v2, 16, v2
	v_add3_u32 v3, v3, v62, s24
	v_and_or_b32 v2, v3, s25, v2
	v_bfe_u32 v3, v4, 16, 1
	v_add3_u32 v3, v4, v3, s24
	v_bfe_u32 v4, v5, 16, 1
	v_lshrrev_b32_e32 v3, 16, v3
	v_add3_u32 v4, v5, v4, s24
	v_and_or_b32 v3, v4, s25, v3
	s_andn2_b64 vcc, exec, s[16:17]
	global_store_dwordx2 v[132:133], v[2:3], off offset:3584
	s_cbranch_vccnz .LBB0_180
	s_waitcnt vmcnt(8)
	v_lshl_add_u64 v[132:133], v[132:133], 0, s[12:13]
	s_mov_b64 s[6:7], 0
	v_mov_b32_e32 v142, v25
	v_mov_b32_e32 v143, v24
	v_mov_b32_e32 v144, v23
	v_mov_b32_e32 v145, v22
	v_mov_b32_e32 v5, v29
	v_mov_b32_e32 v4, v28
	v_mov_b32_e32 v3, v27
	v_mov_b32_e32 v2, v26
	v_mov_b32_e32 v65, v33
	v_mov_b32_e32 v64, v32
	v_mov_b32_e32 v63, v31
	v_mov_b32_e32 v62, v30
	v_mov_b32_e32 v109, v37
	v_mov_b32_e32 v108, v36
	v_mov_b32_e32 v107, v35
	v_mov_b32_e32 v106, v34
	v_mov_b32_e32 v113, v9
	v_mov_b32_e32 v112, v8
	v_mov_b32_e32 v111, v7
	v_mov_b32_e32 v110, v6
	v_mov_b32_e32 v121, v13
	v_mov_b32_e32 v120, v12
	v_mov_b32_e32 v119, v11
	v_mov_b32_e32 v118, v10
	v_mov_b32_e32 v125, v17
	v_mov_b32_e32 v124, v16
	v_mov_b32_e32 v123, v15
	v_mov_b32_e32 v122, v14
	v_mov_b32_e32 v129, v21
	v_mov_b32_e32 v128, v20
	v_mov_b32_e32 v127, v19
	v_mov_b32_e32 v126, v18
	s_branch .LBB0_180

.LBB0_460:
	s_or_b64 exec, exec, s[6:7]
	s_mov_b64 s[6:7], s[0:1]
	s_andn2_b64 vcc, exec, s[48:49]
	s_waitcnt lgkmcnt(0)
	s_barrier
	s_cbranch_vccnz .LBB0_469
	s_load_dwordx4 s[8:11], s[6:7], 0x108
	v_lshlrev_b32_e32 v130, 2, v200
	v_mov_b32_e32 v131, 0
	v_mbcnt_hi_u32_b32 v138, -1, v224
	v_and_b32_e32 v139, 64, v138
	s_waitcnt lgkmcnt(0)
	s_add_u32 s14, s10, 0x194000
	s_addc_u32 s15, s11, 0
	s_ashr_i32 s47, s46, 31
	s_lshl_b64 s[6:7], s[46:47], 13
	s_add_u32 s6, s8, s6
	s_addc_u32 s7, s9, s7
	v_lshl_add_u64 v[2:3], s[6:7], 0, v[130:131]
	global_load_dwordx4 v[126:129], v130, s[6:7] nt
	global_load_dwordx4 v[122:125], v130, s[6:7] offset:1024 nt
	s_movk_i32 s8, 0x1000
	v_add_co_u32_e32 v6, vcc, s8, v2
	v_xor_b32_e32 v140, 1, v138
	s_nop 0
	v_addc_co_u32_e32 v7, vcc, 0, v3, vcc
	global_load_dwordx4 v[2:5], v[6:7], off offset:2048 nt
	global_load_dwordx4 v[114:117], v[6:7], off offset:3072 nt
	global_load_dwordx4 v[118:121], v130, s[6:7] offset:2048 nt
	global_load_dwordx4 v[110:113], v130, s[6:7] offset:3072 nt
	global_load_dwordx4 v[106:109], v[6:7], off nt
	global_load_dwordx4 v[50:53], v[6:7], off offset:1024 nt
	v_mov_b32_e32 v135, v131
	v_mov_b32_e32 v133, v131
	v_add_u32_e32 v131, 64, v139
	v_xor_b32_e32 v141, 2, v138
	v_cmp_lt_i32_e32 vcc, v140, v131
	v_xor_b32_e32 v142, 4, v138
	v_xor_b32_e32 v143, 8, v138
	v_cndmask_b32_e32 v139, v138, v140, vcc
	v_cmp_lt_i32_e32 vcc, v141, v131
	v_xor_b32_e32 v144, 16, v138
	s_lshl_b64 s[28:29], s[46:47], 12
	v_cndmask_b32_e32 v140, v138, v141, vcc
	v_cmp_lt_i32_e32 vcc, v142, v131
	v_xor_b32_e32 v145, 32, v138
	s_add_u32 s10, s10, s28
	v_cndmask_b32_e32 v141, v138, v142, vcc
	v_cmp_lt_i32_e32 vcc, v143, v131
	v_lshlrev_b32_e32 v134, 3, v198
	v_lshlrev_b32_e32 v132, 4, v198
	v_cndmask_b32_e32 v142, v138, v143, vcc
	v_cmp_lt_i32_e32 vcc, v144, v131
	s_addc_u32 s11, s11, s29
	s_mov_b64 s[22:23], 0x9100000
	v_cndmask_b32_e32 v143, v138, v144, vcc
	v_cmp_lt_i32_e32 vcc, v145, v131
	s_mov_b64 s[26:27], 0x3c00
	v_lshl_add_u64 v[132:133], s[6:7], 0, v[132:133]
	v_cndmask_b32_e32 v144, v138, v145, vcc
	v_lshl_add_u64 v[134:135], s[10:11], 0, v[134:135]
	s_mov_b32 s16, -1
	s_mov_b64 s[8:9], 0x2000
	v_mov_b32_e32 v136, 0x358637bd
	s_mov_b32 s17, 0xf800000
	v_mov_b32_e32 v137, 0x260
	s_movk_i32 s18, 0x7fff
	s_mov_b32 s19, 0xffff0000
	s_mov_b64 s[12:13], 0x1000
	s_mov_b32 s21, s46
	v_lshlrev_b32_e32 v131, 2, v139
	v_lshlrev_b32_e32 v138, 2, v140
	v_lshlrev_b32_e32 v139, 2, v141
	v_lshlrev_b32_e32 v140, 2, v142
	v_lshlrev_b32_e32 v141, 2, v143
	v_lshlrev_b32_e32 v142, 2, v144
	v_lshl_add_u64 v[132:133], v[132:133], 0, s[26:27]
	v_lshl_add_u64 v[134:135], v[134:135], 0, s[22:23]
	s_waitcnt vmcnt(0)
	v_mov_b32_e32 v146, v114
	v_mov_b32_e32 v145, v115
	v_mov_b32_e32 v144, v116
	v_mov_b32_e32 v143, v117
	s_branch .LBB0_463

.LBB0_465:
	s_add_i32 s6, s21, 0xfffff000
	s_ashr_i32 s6, s6, 12
	s_add_i32 s6, s6, 1
	s_cmpk_gt_i32 s21, 0xfff
	s_cselect_b32 s6, s6, 0
	s_cmp_eq_u32 s6, s16
	s_cbranch_scc1 .LBB0_467
	s_ashr_i32 s7, s6, 31
	s_lshl_b64 s[22:23], s[6:7], 14
	s_add_u32 s22, s14, s22
	s_addc_u32 s23, s15, s23
	s_add_u32 s26, s22, 0x2000
	s_addc_u32 s27, s23, 0
	v_lshlrev_b32_e32 v54, 2, v1
	v_lshlrev_b32_e32 v55, 2, v199
	v_lshlrev_b32_e32 v66, 2, v219
	v_lshlrev_b32_e32 v67, 2, v220
	v_lshlrev_b32_e32 v74, 2, v221
	v_lshlrev_b32_e32 v82, 2, v222
	v_lshlrev_b32_e32 v102, 2, v223
	global_load_dwordx4 v[38:41], v130, s[22:23] offset:1024
	global_load_dwordx4 v[42:45], v130, s[22:23] offset:2048
	global_load_dwordx4 v[62:65], v54, s[26:27]
	global_load_dwordx4 v[58:61], v55, s[26:27]
	global_load_dwordx4 v[70:73], v130, s[26:27]
	global_load_dwordx4 v[46:49], v130, s[22:23] offset:3072
	global_load_dwordx4 v[78:81], v66, s[26:27]
	s_nop 0
	global_load_dwordx4 v[54:57], v67, s[22:23]
	global_load_dwordx4 v[86:89], v67, s[26:27]
	s_nop 0
	global_load_dwordx4 v[66:69], v74, s[22:23]
	global_load_dwordx4 v[90:93], v74, s[26:27]
	s_nop 0
	global_load_dwordx4 v[74:77], v82, s[22:23]
	global_load_dwordx4 v[98:101], v82, s[26:27]
	s_nop 0
	global_load_dwordx4 v[82:85], v102, s[22:23]
	global_load_dwordx4 v[94:97], v130, s[22:23]
	s_nop 0
	global_load_dwordx4 v[102:105], v102, s[26:27]
	s_waitcnt vmcnt(0)
	s_mov_b32 s16, s6
.LBB0_467:
	v_pk_mul_f32 v[160:161], v[126:127], v[126:127]
	v_pk_mul_f32 v[162:163], v[122:123], v[122:123]
	v_pk_mul_f32 v[156:157], v[128:129], v[128:129]
	v_pk_mul_f32 v[158:159], v[124:125], v[124:125]
	v_mov_b32_e32 v164, v160
	v_mov_b32_e32 v165, v162
	v_mov_b32_e32 v162, v161
	v_pk_mul_f32 v[152:153], v[120:121], v[120:121]
	v_pk_mul_f32 v[154:155], v[118:119], v[118:119]
	v_pk_add_f32 v[160:161], v[164:165], v[162:163]
	v_mov_b32_e32 v162, v156
	v_mov_b32_e32 v163, v158
	v_mov_b32_e32 v158, v157
	v_pk_add_f32 v[156:157], v[162:163], v[158:159]
	v_pk_mov_b32 v[158:159], v[154:155], v[152:153] op_sel:[1,0]
	v_mov_b32_e32 v155, v153
	v_pk_add_f32 v[152:153], v[158:159], v[154:155]
	v_pk_add_f32 v[156:157], v[160:161], v[156:157]
	v_pk_add_f32 v[152:153], v[152:153], v[152:153] op_sel_hi:[0,1]
	v_mul_f32_e32 v152, v110, v110
	v_pk_fma_f32 v[154:155], v[110:111], v[110:111], v[152:153] op_sel_hi:[1,1,0]
	v_mul_f32_e32 v152, v112, v112
	v_pk_add_f32 v[156:157], v[156:157], v[156:157] op_sel_hi:[0,1]
	v_pk_fma_f32 v[158:159], v[112:113], v[112:113], v[152:153] op_sel_hi:[1,1,0]
	v_mul_f32_e32 v154, v106, v106
	v_mul_f32_e32 v158, v107, v107
	v_mul_f32_e32 v152, v108, v108
	v_mul_f32_e32 v156, v109, v109
	v_pk_mul_f32 v[148:149], v[52:53], v[52:53]
	v_pk_mul_f32 v[150:151], v[50:51], v[50:51]
	v_pk_add_f32 v[154:155], v[154:155], v[158:159]
	v_pk_add_f32 v[152:153], v[152:153], v[156:157]
	s_nop 0
	v_pk_add_f32 v[152:153], v[154:155], v[152:153]
	v_pk_mov_b32 v[154:155], v[150:151], v[148:149] op_sel:[1,0]
	v_mov_b32_e32 v151, v149
	v_pk_add_f32 v[148:149], v[154:155], v[150:151]
	v_pk_add_f32 v[152:153], v[152:153], v[152:153] op_sel_hi:[0,1]
	v_pk_add_f32 v[148:149], v[148:149], v[148:149] op_sel_hi:[0,1]
	v_mul_f32_e32 v148, v2, v2
	v_pk_fma_f32 v[150:151], v[2:3], v[2:3], v[148:149] op_sel_hi:[1,1,0]
	v_mul_f32_e32 v148, v4, v4
	v_pk_fma_f32 v[154:155], v[4:5], v[4:5], v[148:149] op_sel_hi:[1,1,0]
	v_mul_f32_e32 v150, v146, v146
	v_mul_f32_e32 v154, v145, v145
	v_mul_f32_e32 v148, v144, v144
	v_mul_f32_e32 v152, v143, v143
	v_pk_add_f32 v[144:145], v[150:151], v[154:155]
	v_pk_add_f32 v[146:147], v[148:149], v[152:153]
	s_nop 0
	v_pk_add_f32 v[144:145], v[144:145], v[146:147]
	s_nop 0
	v_add_f32_e32 v143, v144, v145
	ds_bpermute_b32 v144, v131, v143
	s_waitcnt lgkmcnt(0)
	v_add_f32_e32 v143, v143, v144
	ds_bpermute_b32 v144, v138, v143
	s_waitcnt lgkmcnt(0)
	v_add_f32_e32 v143, v143, v144
	ds_bpermute_b32 v144, v139, v143
	s_waitcnt lgkmcnt(0)
	v_add_f32_e32 v143, v143, v144
	ds_bpermute_b32 v144, v140, v143
	s_waitcnt lgkmcnt(0)
	v_add_f32_e32 v143, v143, v144
	ds_bpermute_b32 v144, v141, v143
	s_waitcnt lgkmcnt(0)
	v_add_f32_e32 v143, v143, v144
	ds_bpermute_b32 v144, v142, v143
	s_waitcnt lgkmcnt(0)
	v_add_f32_e32 v143, v143, v144
	v_fmamk_f32 v143, v143, 0x3a000000, v136
	v_mul_f32_e32 v144, 0x4f800000, v143
	v_cmp_gt_f32_e32 vcc, s17, v143
	s_nop 1
	v_cndmask_b32_e32 v143, v143, v144, vcc
	v_sqrt_f32_e32 v144, v143
	s_nop 0
	v_add_u32_e32 v145, -1, v144
	v_fma_f32 v146, -v145, v144, v143
	v_cmp_ge_f32_e64 s[6:7], 0, v146
	v_add_u32_e32 v146, 1, v144
	s_nop 0
	v_cndmask_b32_e64 v145, v144, v145, s[6:7]
	v_fma_f32 v144, -v146, v144, v143
	v_cmp_lt_f32_e64 s[6:7], 0, v144
	s_nop 1
	v_cndmask_b32_e64 v144, v145, v146, s[6:7]
	v_mul_f32_e32 v145, 0x37800000, v144
	v_cndmask_b32_e32 v144, v144, v145, vcc
	v_cmp_class_f32_e32 vcc, v143, v137
	s_nop 1
	v_cndmask_b32_e32 v143, v144, v143, vcc
	v_div_scale_f32 v144, s[6:7], v143, v143, 1.0
	v_rcp_f32_e32 v145, v144
	s_mov_b64 s[6:7], -1
	v_fma_f32 v146, -v144, v145, 1.0
	v_fmac_f32_e32 v145, v146, v145
	v_div_scale_f32 v146, vcc, 1.0, v143, 1.0
	v_mul_f32_e32 v147, v146, v145
	v_fma_f32 v148, -v144, v147, v146
	v_fmac_f32_e32 v147, v148, v145
	v_fma_f32 v144, -v144, v147, v146
	v_div_fmas_f32 v144, v144, v145, v147
	v_div_fixup_f32 v144, v144, v143, 1.0
	v_pk_mul_f32 v[126:127], v[126:127], v[144:145] op_sel_hi:[1,0]
	v_pk_mul_f32 v[128:129], v[128:129], v[144:145] op_sel_hi:[1,0]
	v_pk_fma_f32 v[126:127], v[94:95], v[126:127], v[70:71]
	v_pk_fma_f32 v[128:129], v[96:97], v[128:129], v[72:73]
	v_bfe_u32 v143, v126, 16, 1
	v_add3_u32 v126, v126, v143, s18
	v_bfe_u32 v143, v127, 16, 1
	v_lshrrev_b32_e32 v126, 16, v126
	v_add3_u32 v127, v127, v143, s18
	v_and_or_b32 v126, v127, s19, v126
	v_bfe_u32 v127, v128, 16, 1
	v_add3_u32 v127, v128, v127, s18
	v_bfe_u32 v128, v129, 16, 1
	v_lshrrev_b32_e32 v127, 16, v127
	v_add3_u32 v128, v129, v128, s18
	v_pk_mul_f32 v[122:123], v[122:123], v[144:145] op_sel_hi:[1,0]
	v_and_or_b32 v127, v128, s19, v127
	v_pk_fma_f32 v[122:123], v[38:39], v[122:123], v[62:63]
	global_store_dwordx2 v[134:135], v[126:127], off
	v_bfe_u32 v126, v122, 16, 1
	v_pk_mul_f32 v[124:125], v[124:125], v[144:145] op_sel_hi:[1,0]
	v_add3_u32 v122, v122, v126, s18
	v_bfe_u32 v126, v123, 16, 1
	v_pk_fma_f32 v[124:125], v[40:41], v[124:125], v[64:65]
	v_lshrrev_b32_e32 v122, 16, v122
	v_add3_u32 v123, v123, v126, s18
	v_and_or_b32 v122, v123, s19, v122
	v_bfe_u32 v123, v124, 16, 1
	v_add3_u32 v123, v124, v123, s18
	v_bfe_u32 v124, v125, 16, 1
	v_lshrrev_b32_e32 v123, 16, v123
	v_add3_u32 v124, v125, v124, s18
	v_pk_mul_f32 v[118:119], v[118:119], v[144:145] op_sel_hi:[1,0]
	v_and_or_b32 v123, v124, s19, v123
	v_pk_fma_f32 v[118:119], v[42:43], v[118:119], v[58:59]
	global_store_dwordx2 v[134:135], v[122:123], off offset:512
	v_bfe_u32 v122, v118, 16, 1
	v_pk_mul_f32 v[120:121], v[120:121], v[144:145] op_sel_hi:[1,0]
	v_add3_u32 v118, v118, v122, s18
	v_bfe_u32 v122, v119, 16, 1
	v_pk_fma_f32 v[120:121], v[44:45], v[120:121], v[60:61]
	v_lshrrev_b32_e32 v118, 16, v118
	v_add3_u32 v119, v119, v122, s18
	v_and_or_b32 v118, v119, s19, v118
	v_bfe_u32 v119, v120, 16, 1
	v_add3_u32 v119, v120, v119, s18
	v_bfe_u32 v120, v121, 16, 1
	v_lshrrev_b32_e32 v119, 16, v119
	v_add3_u32 v120, v121, v120, s18
	v_pk_mul_f32 v[110:111], v[110:111], v[144:145] op_sel_hi:[1,0]
	v_and_or_b32 v119, v120, s19, v119
	v_pk_fma_f32 v[110:111], v[46:47], v[110:111], v[78:79]
	global_store_dwordx2 v[134:135], v[118:119], off offset:1024
	v_bfe_u32 v118, v110, 16, 1
	v_pk_mul_f32 v[112:113], v[112:113], v[144:145] op_sel_hi:[1,0]
	v_add3_u32 v110, v110, v118, s18
	v_bfe_u32 v118, v111, 16, 1
	v_pk_fma_f32 v[112:113], v[48:49], v[112:113], v[80:81]
	v_lshrrev_b32_e32 v110, 16, v110
	v_add3_u32 v111, v111, v118, s18
	v_and_or_b32 v110, v111, s19, v110
	v_bfe_u32 v111, v112, 16, 1
	v_add3_u32 v111, v112, v111, s18
	v_bfe_u32 v112, v113, 16, 1
	v_lshrrev_b32_e32 v111, 16, v111
	v_add3_u32 v112, v113, v112, s18
	v_pk_mul_f32 v[106:107], v[106:107], v[144:145] op_sel_hi:[1,0]
	v_and_or_b32 v111, v112, s19, v111
	v_pk_fma_f32 v[106:107], v[54:55], v[106:107], v[86:87]
	global_store_dwordx2 v[134:135], v[110:111], off offset:1536
	v_bfe_u32 v110, v106, 16, 1
	v_pk_mul_f32 v[108:109], v[108:109], v[144:145] op_sel_hi:[1,0]
	v_add3_u32 v106, v106, v110, s18
	v_bfe_u32 v110, v107, 16, 1
	v_pk_fma_f32 v[108:109], v[56:57], v[108:109], v[88:89]
	v_lshrrev_b32_e32 v106, 16, v106
	v_add3_u32 v107, v107, v110, s18
	v_and_or_b32 v106, v107, s19, v106
	v_bfe_u32 v107, v108, 16, 1
	v_add3_u32 v107, v108, v107, s18
	v_bfe_u32 v108, v109, 16, 1
	v_lshrrev_b32_e32 v107, 16, v107
	v_add3_u32 v108, v109, v108, s18
	v_pk_mul_f32 v[50:51], v[50:51], v[144:145] op_sel_hi:[1,0]
	v_and_or_b32 v107, v108, s19, v107
	v_pk_fma_f32 v[50:51], v[66:67], v[50:51], v[90:91]
	global_store_dwordx2 v[134:135], v[106:107], off offset:2048
	v_bfe_u32 v106, v50, 16, 1
	v_pk_mul_f32 v[52:53], v[52:53], v[144:145] op_sel_hi:[1,0]
	v_add3_u32 v50, v50, v106, s18
	v_bfe_u32 v106, v51, 16, 1
	v_pk_fma_f32 v[52:53], v[68:69], v[52:53], v[92:93]
	v_lshrrev_b32_e32 v50, 16, v50
	v_add3_u32 v51, v51, v106, s18
	v_and_or_b32 v50, v51, s19, v50
	v_bfe_u32 v51, v52, 16, 1
	v_add3_u32 v51, v52, v51, s18
	v_bfe_u32 v52, v53, 16, 1
	v_lshrrev_b32_e32 v51, 16, v51
	v_add3_u32 v52, v53, v52, s18
	v_pk_mul_f32 v[2:3], v[2:3], v[144:145] op_sel_hi:[1,0]
	v_and_or_b32 v51, v52, s19, v51
	v_pk_fma_f32 v[2:3], v[74:75], v[2:3], v[98:99]
	global_store_dwordx2 v[134:135], v[50:51], off offset:2560
	v_bfe_u32 v50, v2, 16, 1
	v_pk_mul_f32 v[4:5], v[4:5], v[144:145] op_sel_hi:[1,0]
	v_add3_u32 v2, v2, v50, s18
	v_bfe_u32 v50, v3, 16, 1
	v_pk_fma_f32 v[4:5], v[76:77], v[4:5], v[100:101]
	v_lshrrev_b32_e32 v2, 16, v2
	v_add3_u32 v3, v3, v50, s18
	v_and_or_b32 v2, v3, s19, v2
	v_bfe_u32 v3, v4, 16, 1
	v_add3_u32 v3, v4, v3, s18
	v_bfe_u32 v4, v5, 16, 1
	v_lshrrev_b32_e32 v3, 16, v3
	v_add3_u32 v4, v5, v4, s18
	v_and_or_b32 v3, v4, s19, v3
	global_store_dwordx2 v[134:135], v[2:3], off offset:3072
	v_pk_mul_f32 v[2:3], v[114:115], v[144:145] op_sel_hi:[1,0]
	v_pk_mul_f32 v[4:5], v[116:117], v[144:145] op_sel_hi:[1,0]
	v_pk_fma_f32 v[2:3], v[82:83], v[2:3], v[102:103]
	v_pk_fma_f32 v[4:5], v[84:85], v[4:5], v[104:105]
	v_bfe_u32 v50, v2, 16, 1
	v_add3_u32 v2, v2, v50, s18
	v_bfe_u32 v50, v3, 16, 1
	v_lshrrev_b32_e32 v2, 16, v2
	v_add3_u32 v3, v3, v50, s18
	v_and_or_b32 v2, v3, s19, v2
	v_bfe_u32 v3, v4, 16, 1
	v_add3_u32 v3, v4, v3, s18
	v_bfe_u32 v4, v5, 16, 1
	v_lshrrev_b32_e32 v3, 16, v3
	v_add3_u32 v4, v5, v4, s18
	v_and_or_b32 v3, v4, s19, v3
	s_andn2_b64 vcc, exec, s[10:11]
	global_store_dwordx2 v[134:135], v[2:3], off offset:3584
	s_cbranch_vccnz .LBB0_462
	s_waitcnt vmcnt(8)
	v_lshl_add_u64 v[134:135], v[134:135], 0, s[12:13]
	v_lshl_add_u64 v[132:133], v[132:133], 0, s[8:9]
	s_mov_b64 s[6:7], 0
	v_mov_b32_e32 v143, v9
	v_mov_b32_e32 v144, v8
	v_mov_b32_e32 v145, v7
	v_mov_b32_e32 v146, v6
	v_mov_b32_e32 v5, v13
	v_mov_b32_e32 v4, v12
	v_mov_b32_e32 v3, v11
	v_mov_b32_e32 v2, v10
	v_mov_b32_e32 v53, v17
	v_mov_b32_e32 v52, v16
	v_mov_b32_e32 v51, v15
	v_mov_b32_e32 v50, v14
	v_mov_b32_e32 v109, v21
	v_mov_b32_e32 v108, v20
	v_mov_b32_e32 v107, v19
	v_mov_b32_e32 v106, v18
	v_mov_b32_e32 v113, v25
	v_mov_b32_e32 v112, v24
	v_mov_b32_e32 v111, v23
	v_mov_b32_e32 v110, v22
	v_mov_b32_e32 v121, v29
	v_mov_b32_e32 v120, v28
	v_mov_b32_e32 v119, v27
	v_mov_b32_e32 v118, v26
	v_mov_b32_e32 v125, v33
	v_mov_b32_e32 v124, v32
	v_mov_b32_e32 v123, v31
	v_mov_b32_e32 v122, v30
	v_mov_b32_e32 v129, v37
	v_mov_b32_e32 v128, v36
	v_mov_b32_e32 v127, v35
	v_mov_b32_e32 v126, v34
	s_branch .LBB0_462

.LBB0_1226:
	s_or_b64 exec, exec, s[6:7]
	s_mov_b64 s[6:7], s[0:1]
	s_and_b64 vcc, exec, s[48:49]
	s_waitcnt lgkmcnt(0)
	s_barrier
	s_cbranch_vccz .LBB0_1235
	s_load_dwordx4 s[8:11], s[6:7], 0x108
	s_waitcnt vmcnt(14)
	v_lshlrev_b32_e32 v130, 2, v200
	v_mov_b32_e32 v131, 0
	v_mbcnt_hi_u32_b32 v138, -1, v224
	v_and_b32_e32 v139, 64, v138
	s_waitcnt lgkmcnt(0)
	s_add_u32 s13, s10, 0x1a8000
	s_addc_u32 s18, s11, 0
	s_ashr_i32 s47, s46, 31
	s_lshl_b64 s[6:7], s[46:47], 13
	s_add_u32 s6, s8, s6
	s_addc_u32 s7, s9, s7
	v_lshl_add_u64 v[2:3], s[6:7], 0, v[130:131]
	global_load_dwordx4 v[126:129], v130, s[6:7] nt
	global_load_dwordx4 v[122:125], v130, s[6:7] offset:1024 nt
	s_movk_i32 s8, 0x1000
	v_add_co_u32_e32 v6, vcc, s8, v2
	v_xor_b32_e32 v140, 1, v138
	s_nop 0
	v_addc_co_u32_e32 v7, vcc, 0, v3, vcc
	global_load_dwordx4 v[2:5], v[6:7], off offset:2048 nt
	global_load_dwordx4 v[114:117], v[6:7], off offset:3072 nt
	global_load_dwordx4 v[118:121], v130, s[6:7] offset:2048 nt
	global_load_dwordx4 v[110:113], v130, s[6:7] offset:3072 nt
	global_load_dwordx4 v[106:109], v[6:7], off nt
	global_load_dwordx4 v[50:53], v[6:7], off offset:1024 nt
	s_waitcnt vmcnt(17)
	v_mov_b32_e32 v135, v131
	v_mov_b32_e32 v133, v131
	v_add_u32_e32 v131, 64, v139
	v_xor_b32_e32 v141, 2, v138
	v_cmp_lt_i32_e32 vcc, v140, v131
	v_xor_b32_e32 v142, 4, v138
	v_xor_b32_e32 v143, 8, v138
	v_cndmask_b32_e32 v139, v138, v140, vcc
	v_cmp_lt_i32_e32 vcc, v141, v131
	v_xor_b32_e32 v144, 16, v138
	s_lshl_b64 s[28:29], s[46:47], 12
	v_cndmask_b32_e32 v140, v138, v141, vcc
	v_cmp_lt_i32_e32 vcc, v142, v131
	v_xor_b32_e32 v145, 32, v138
	s_add_u32 s10, s10, s28
	v_cndmask_b32_e32 v141, v138, v142, vcc
	v_cmp_lt_i32_e32 vcc, v143, v131
	v_lshlrev_b32_e32 v134, 3, v198
	v_lshlrev_b32_e32 v132, 4, v198
	v_cndmask_b32_e32 v142, v138, v143, vcc
	v_cmp_lt_i32_e32 vcc, v144, v131
	s_addc_u32 s11, s11, s29
	s_mov_b64 s[24:25], 0x9100000
	v_cndmask_b32_e32 v143, v138, v144, vcc
	v_cmp_lt_i32_e32 vcc, v145, v131
	s_mov_b64 s[26:27], 0x3c00
	v_lshl_add_u64 v[132:133], s[6:7], 0, v[132:133]
	v_cndmask_b32_e32 v144, v138, v145, vcc
	v_lshl_add_u64 v[134:135], s[10:11], 0, v[134:135]
	s_mov_b32 s19, -1
	s_mov_b64 s[8:9], 0x2000
	v_mov_b32_e32 v136, 0x358637bd
	s_mov_b32 s20, 0xf800000
	v_mov_b32_e32 v137, 0x260
	s_movk_i32 s21, 0x7fff
	s_mov_b32 s22, 0xffff0000
	s_mov_b64 s[16:17], 0x1000
	v_lshlrev_b32_e32 v131, 2, v139
	v_lshlrev_b32_e32 v138, 2, v140
	v_lshlrev_b32_e32 v139, 2, v141
	v_lshlrev_b32_e32 v140, 2, v142
	v_lshlrev_b32_e32 v141, 2, v143
	v_lshlrev_b32_e32 v142, 2, v144
	v_lshl_add_u64 v[132:133], v[132:133], 0, s[26:27]
	v_lshl_add_u64 v[134:135], v[134:135], 0, s[24:25]
	s_waitcnt vmcnt(0)
	v_mov_b32_e32 v146, v114
	v_mov_b32_e32 v145, v115
	v_mov_b32_e32 v144, v116
	v_mov_b32_e32 v143, v117
	s_branch .LBB0_1229

.LBB0_1231:
	s_add_i32 s6, s46, 0xfffff000
	s_ashr_i32 s6, s6, 12
	s_add_i32 s6, s6, 1
	s_cmpk_gt_i32 s46, 0xfff
	s_cselect_b32 s6, s6, 0
	s_cmp_eq_u32 s6, s19
	s_cbranch_scc1 .LBB0_1233
	s_ashr_i32 s7, s6, 31
	s_lshl_b64 s[24:25], s[6:7], 14
	s_add_u32 s24, s13, s24
	s_addc_u32 s25, s18, s25
	s_add_u32 s26, s24, 0x2000
	s_addc_u32 s27, s25, 0
	v_lshlrev_b32_e32 v54, 2, v1
	v_lshlrev_b32_e32 v55, 2, v199
	v_lshlrev_b32_e32 v66, 2, v219
	v_lshlrev_b32_e32 v67, 2, v220
	v_lshlrev_b32_e32 v74, 2, v221
	v_lshlrev_b32_e32 v82, 2, v222
	v_lshlrev_b32_e32 v102, 2, v223
	global_load_dwordx4 v[38:41], v130, s[24:25] offset:1024
	global_load_dwordx4 v[42:45], v130, s[24:25] offset:2048
	global_load_dwordx4 v[62:65], v54, s[26:27]
	global_load_dwordx4 v[58:61], v55, s[26:27]
	global_load_dwordx4 v[70:73], v130, s[26:27]
	global_load_dwordx4 v[46:49], v130, s[24:25] offset:3072
	global_load_dwordx4 v[78:81], v66, s[26:27]
	s_nop 0
	global_load_dwordx4 v[54:57], v67, s[24:25]
	global_load_dwordx4 v[86:89], v67, s[26:27]
	s_nop 0
	global_load_dwordx4 v[66:69], v74, s[24:25]
	global_load_dwordx4 v[90:93], v74, s[26:27]
	s_nop 0
	global_load_dwordx4 v[74:77], v82, s[24:25]
	global_load_dwordx4 v[98:101], v82, s[26:27]
	s_nop 0
	global_load_dwordx4 v[82:85], v102, s[24:25]
	global_load_dwordx4 v[94:97], v130, s[24:25]
	s_nop 0
	global_load_dwordx4 v[102:105], v102, s[26:27]
	s_waitcnt vmcnt(0)
	s_mov_b32 s19, s6
.LBB0_1233:
	v_pk_mul_f32 v[160:161], v[126:127], v[126:127]
	v_pk_mul_f32 v[162:163], v[122:123], v[122:123]
	v_pk_mul_f32 v[156:157], v[128:129], v[128:129]
	v_pk_mul_f32 v[158:159], v[124:125], v[124:125]
	v_mov_b32_e32 v164, v160
	v_mov_b32_e32 v165, v162
	v_mov_b32_e32 v162, v161
	v_pk_mul_f32 v[152:153], v[120:121], v[120:121]
	v_pk_mul_f32 v[154:155], v[118:119], v[118:119]
	v_pk_add_f32 v[160:161], v[164:165], v[162:163]
	v_mov_b32_e32 v162, v156
	v_mov_b32_e32 v163, v158
	v_mov_b32_e32 v158, v157
	v_pk_add_f32 v[156:157], v[162:163], v[158:159]
	v_pk_mov_b32 v[158:159], v[154:155], v[152:153] op_sel:[1,0]
	v_mov_b32_e32 v155, v153
	v_pk_add_f32 v[152:153], v[158:159], v[154:155]
	v_pk_add_f32 v[156:157], v[160:161], v[156:157]
	v_pk_add_f32 v[152:153], v[152:153], v[152:153] op_sel_hi:[0,1]
	v_mul_f32_e32 v152, v110, v110
	v_pk_fma_f32 v[154:155], v[110:111], v[110:111], v[152:153] op_sel_hi:[1,1,0]
	v_mul_f32_e32 v152, v112, v112
	v_pk_add_f32 v[156:157], v[156:157], v[156:157] op_sel_hi:[0,1]
	v_pk_fma_f32 v[158:159], v[112:113], v[112:113], v[152:153] op_sel_hi:[1,1,0]
	v_mul_f32_e32 v154, v106, v106
	v_mul_f32_e32 v158, v107, v107
	v_mul_f32_e32 v152, v108, v108
	v_mul_f32_e32 v156, v109, v109
	v_pk_mul_f32 v[148:149], v[52:53], v[52:53]
	v_pk_mul_f32 v[150:151], v[50:51], v[50:51]
	v_pk_add_f32 v[154:155], v[154:155], v[158:159]
	v_pk_add_f32 v[152:153], v[152:153], v[156:157]
	s_nop 0
	v_pk_add_f32 v[152:153], v[154:155], v[152:153]
	v_pk_mov_b32 v[154:155], v[150:151], v[148:149] op_sel:[1,0]
	v_mov_b32_e32 v151, v149
	v_pk_add_f32 v[148:149], v[154:155], v[150:151]
	v_pk_add_f32 v[152:153], v[152:153], v[152:153] op_sel_hi:[0,1]
	v_pk_add_f32 v[148:149], v[148:149], v[148:149] op_sel_hi:[0,1]
	v_mul_f32_e32 v148, v2, v2
	v_pk_fma_f32 v[150:151], v[2:3], v[2:3], v[148:149] op_sel_hi:[1,1,0]
	v_mul_f32_e32 v148, v4, v4
	v_pk_fma_f32 v[154:155], v[4:5], v[4:5], v[148:149] op_sel_hi:[1,1,0]
	v_mul_f32_e32 v150, v146, v146
	v_mul_f32_e32 v154, v145, v145
	v_mul_f32_e32 v148, v144, v144
	v_mul_f32_e32 v152, v143, v143
	v_pk_add_f32 v[144:145], v[150:151], v[154:155]
	v_pk_add_f32 v[146:147], v[148:149], v[152:153]
	s_nop 0
	v_pk_add_f32 v[144:145], v[144:145], v[146:147]
	s_nop 0
	v_add_f32_e32 v143, v144, v145
	ds_bpermute_b32 v144, v131, v143
	s_waitcnt lgkmcnt(0)
	v_add_f32_e32 v143, v143, v144
	ds_bpermute_b32 v144, v138, v143
	s_waitcnt lgkmcnt(0)
	v_add_f32_e32 v143, v143, v144
	ds_bpermute_b32 v144, v139, v143
	s_waitcnt lgkmcnt(0)
	v_add_f32_e32 v143, v143, v144
	ds_bpermute_b32 v144, v140, v143
	s_waitcnt lgkmcnt(0)
	v_add_f32_e32 v143, v143, v144
	ds_bpermute_b32 v144, v141, v143
	s_waitcnt lgkmcnt(0)
	v_add_f32_e32 v143, v143, v144
	ds_bpermute_b32 v144, v142, v143
	s_waitcnt lgkmcnt(0)
	v_add_f32_e32 v143, v143, v144
	v_fmamk_f32 v143, v143, 0x3a000000, v136
	v_mul_f32_e32 v144, 0x4f800000, v143
	v_cmp_gt_f32_e32 vcc, s20, v143
	s_nop 1
	v_cndmask_b32_e32 v143, v143, v144, vcc
	v_sqrt_f32_e32 v144, v143
	s_nop 0
	v_add_u32_e32 v145, -1, v144
	v_fma_f32 v146, -v145, v144, v143
	v_cmp_ge_f32_e64 s[6:7], 0, v146
	v_add_u32_e32 v146, 1, v144
	s_nop 0
	v_cndmask_b32_e64 v145, v144, v145, s[6:7]
	v_fma_f32 v144, -v146, v144, v143
	v_cmp_lt_f32_e64 s[6:7], 0, v144
	s_nop 1
	v_cndmask_b32_e64 v144, v145, v146, s[6:7]
	v_mul_f32_e32 v145, 0x37800000, v144
	v_cndmask_b32_e32 v144, v144, v145, vcc
	v_cmp_class_f32_e32 vcc, v143, v137
	s_nop 1
	v_cndmask_b32_e32 v143, v144, v143, vcc
	v_div_scale_f32 v144, s[6:7], v143, v143, 1.0
	v_rcp_f32_e32 v145, v144
	s_mov_b64 s[6:7], -1
	v_fma_f32 v146, -v144, v145, 1.0
	v_fmac_f32_e32 v145, v146, v145
	v_div_scale_f32 v146, vcc, 1.0, v143, 1.0
	v_mul_f32_e32 v147, v146, v145
	v_fma_f32 v148, -v144, v147, v146
	v_fmac_f32_e32 v147, v148, v145
	v_fma_f32 v144, -v144, v147, v146
	v_div_fmas_f32 v144, v144, v145, v147
	v_div_fixup_f32 v144, v144, v143, 1.0
	v_pk_mul_f32 v[126:127], v[126:127], v[144:145] op_sel_hi:[1,0]
	v_pk_mul_f32 v[128:129], v[128:129], v[144:145] op_sel_hi:[1,0]
	v_pk_fma_f32 v[126:127], v[94:95], v[126:127], v[70:71]
	v_pk_fma_f32 v[128:129], v[96:97], v[128:129], v[72:73]
	v_bfe_u32 v143, v126, 16, 1
	v_add3_u32 v126, v126, v143, s21
	v_bfe_u32 v143, v127, 16, 1
	v_lshrrev_b32_e32 v126, 16, v126
	v_add3_u32 v127, v127, v143, s21
	v_and_or_b32 v126, v127, s22, v126
	v_bfe_u32 v127, v128, 16, 1
	v_add3_u32 v127, v128, v127, s21
	v_bfe_u32 v128, v129, 16, 1
	v_lshrrev_b32_e32 v127, 16, v127
	v_add3_u32 v128, v129, v128, s21
	v_pk_mul_f32 v[122:123], v[122:123], v[144:145] op_sel_hi:[1,0]
	v_and_or_b32 v127, v128, s22, v127
	v_pk_fma_f32 v[122:123], v[38:39], v[122:123], v[62:63]
	global_store_dwordx2 v[134:135], v[126:127], off
	v_bfe_u32 v126, v122, 16, 1
	v_pk_mul_f32 v[124:125], v[124:125], v[144:145] op_sel_hi:[1,0]
	v_add3_u32 v122, v122, v126, s21
	v_bfe_u32 v126, v123, 16, 1
	v_pk_fma_f32 v[124:125], v[40:41], v[124:125], v[64:65]
	v_lshrrev_b32_e32 v122, 16, v122
	v_add3_u32 v123, v123, v126, s21
	v_and_or_b32 v122, v123, s22, v122
	v_bfe_u32 v123, v124, 16, 1
	v_add3_u32 v123, v124, v123, s21
	v_bfe_u32 v124, v125, 16, 1
	v_lshrrev_b32_e32 v123, 16, v123
	v_add3_u32 v124, v125, v124, s21
	v_pk_mul_f32 v[118:119], v[118:119], v[144:145] op_sel_hi:[1,0]
	v_and_or_b32 v123, v124, s22, v123
	v_pk_fma_f32 v[118:119], v[42:43], v[118:119], v[58:59]
	global_store_dwordx2 v[134:135], v[122:123], off offset:512
	v_bfe_u32 v122, v118, 16, 1
	v_pk_mul_f32 v[120:121], v[120:121], v[144:145] op_sel_hi:[1,0]
	v_add3_u32 v118, v118, v122, s21
	v_bfe_u32 v122, v119, 16, 1
	v_pk_fma_f32 v[120:121], v[44:45], v[120:121], v[60:61]
	v_lshrrev_b32_e32 v118, 16, v118
	v_add3_u32 v119, v119, v122, s21
	v_and_or_b32 v118, v119, s22, v118
	v_bfe_u32 v119, v120, 16, 1
	v_add3_u32 v119, v120, v119, s21
	v_bfe_u32 v120, v121, 16, 1
	v_lshrrev_b32_e32 v119, 16, v119
	v_add3_u32 v120, v121, v120, s21
	v_pk_mul_f32 v[110:111], v[110:111], v[144:145] op_sel_hi:[1,0]
	v_and_or_b32 v119, v120, s22, v119
	v_pk_fma_f32 v[110:111], v[46:47], v[110:111], v[78:79]
	global_store_dwordx2 v[134:135], v[118:119], off offset:1024
	v_bfe_u32 v118, v110, 16, 1
	v_pk_mul_f32 v[112:113], v[112:113], v[144:145] op_sel_hi:[1,0]
	v_add3_u32 v110, v110, v118, s21
	v_bfe_u32 v118, v111, 16, 1
	v_pk_fma_f32 v[112:113], v[48:49], v[112:113], v[80:81]
	v_lshrrev_b32_e32 v110, 16, v110
	v_add3_u32 v111, v111, v118, s21
	v_and_or_b32 v110, v111, s22, v110
	v_bfe_u32 v111, v112, 16, 1
	v_add3_u32 v111, v112, v111, s21
	v_bfe_u32 v112, v113, 16, 1
	v_lshrrev_b32_e32 v111, 16, v111
	v_add3_u32 v112, v113, v112, s21
	v_pk_mul_f32 v[106:107], v[106:107], v[144:145] op_sel_hi:[1,0]
	v_and_or_b32 v111, v112, s22, v111
	v_pk_fma_f32 v[106:107], v[54:55], v[106:107], v[86:87]
	global_store_dwordx2 v[134:135], v[110:111], off offset:1536
	v_bfe_u32 v110, v106, 16, 1
	v_pk_mul_f32 v[108:109], v[108:109], v[144:145] op_sel_hi:[1,0]
	v_add3_u32 v106, v106, v110, s21
	v_bfe_u32 v110, v107, 16, 1
	v_pk_fma_f32 v[108:109], v[56:57], v[108:109], v[88:89]
	v_lshrrev_b32_e32 v106, 16, v106
	v_add3_u32 v107, v107, v110, s21
	v_and_or_b32 v106, v107, s22, v106
	v_bfe_u32 v107, v108, 16, 1
	v_add3_u32 v107, v108, v107, s21
	v_bfe_u32 v108, v109, 16, 1
	v_lshrrev_b32_e32 v107, 16, v107
	v_add3_u32 v108, v109, v108, s21
	v_pk_mul_f32 v[50:51], v[50:51], v[144:145] op_sel_hi:[1,0]
	v_and_or_b32 v107, v108, s22, v107
	v_pk_fma_f32 v[50:51], v[66:67], v[50:51], v[90:91]
	global_store_dwordx2 v[134:135], v[106:107], off offset:2048
	v_bfe_u32 v106, v50, 16, 1
	v_pk_mul_f32 v[52:53], v[52:53], v[144:145] op_sel_hi:[1,0]
	v_add3_u32 v50, v50, v106, s21
	v_bfe_u32 v106, v51, 16, 1
	v_pk_fma_f32 v[52:53], v[68:69], v[52:53], v[92:93]
	v_lshrrev_b32_e32 v50, 16, v50
	v_add3_u32 v51, v51, v106, s21
	v_and_or_b32 v50, v51, s22, v50
	v_bfe_u32 v51, v52, 16, 1
	v_add3_u32 v51, v52, v51, s21
	v_bfe_u32 v52, v53, 16, 1
	v_lshrrev_b32_e32 v51, 16, v51
	v_add3_u32 v52, v53, v52, s21
	v_pk_mul_f32 v[2:3], v[2:3], v[144:145] op_sel_hi:[1,0]
	v_and_or_b32 v51, v52, s22, v51
	v_pk_fma_f32 v[2:3], v[74:75], v[2:3], v[98:99]
	global_store_dwordx2 v[134:135], v[50:51], off offset:2560
	v_bfe_u32 v50, v2, 16, 1
	v_pk_mul_f32 v[4:5], v[4:5], v[144:145] op_sel_hi:[1,0]
	v_add3_u32 v2, v2, v50, s21
	v_bfe_u32 v50, v3, 16, 1
	v_pk_fma_f32 v[4:5], v[76:77], v[4:5], v[100:101]
	v_lshrrev_b32_e32 v2, 16, v2
	v_add3_u32 v3, v3, v50, s21
	v_and_or_b32 v2, v3, s22, v2
	v_bfe_u32 v3, v4, 16, 1
	v_add3_u32 v3, v4, v3, s21
	v_bfe_u32 v4, v5, 16, 1
	v_lshrrev_b32_e32 v3, 16, v3
	v_add3_u32 v4, v5, v4, s21
	v_and_or_b32 v3, v4, s22, v3
	global_store_dwordx2 v[134:135], v[2:3], off offset:3072
	v_pk_mul_f32 v[2:3], v[114:115], v[144:145] op_sel_hi:[1,0]
	v_pk_mul_f32 v[4:5], v[116:117], v[144:145] op_sel_hi:[1,0]
	v_pk_fma_f32 v[2:3], v[82:83], v[2:3], v[102:103]
	v_pk_fma_f32 v[4:5], v[84:85], v[4:5], v[104:105]
	v_bfe_u32 v50, v2, 16, 1
	v_add3_u32 v2, v2, v50, s21
	v_bfe_u32 v50, v3, 16, 1
	v_lshrrev_b32_e32 v2, 16, v2
	v_add3_u32 v3, v3, v50, s21
	v_and_or_b32 v2, v3, s22, v2
	v_bfe_u32 v3, v4, 16, 1
	v_add3_u32 v3, v4, v3, s21
	v_bfe_u32 v4, v5, 16, 1
	v_lshrrev_b32_e32 v3, 16, v3
	v_add3_u32 v4, v5, v4, s21
	v_and_or_b32 v3, v4, s22, v3
	s_andn2_b64 vcc, exec, s[10:11]
	global_store_dwordx2 v[134:135], v[2:3], off offset:3584
	s_cbranch_vccnz .LBB0_1228
	s_waitcnt vmcnt(8)
	v_lshl_add_u64 v[134:135], v[134:135], 0, s[16:17]
	v_lshl_add_u64 v[132:133], v[132:133], 0, s[8:9]
	s_mov_b64 s[6:7], 0
	v_mov_b32_e32 v143, v9
	v_mov_b32_e32 v144, v8
	v_mov_b32_e32 v145, v7
	v_mov_b32_e32 v146, v6
	v_mov_b32_e32 v5, v13
	v_mov_b32_e32 v4, v12
	v_mov_b32_e32 v3, v11
	v_mov_b32_e32 v2, v10
	v_mov_b32_e32 v53, v17
	v_mov_b32_e32 v52, v16
	v_mov_b32_e32 v51, v15
	v_mov_b32_e32 v50, v14
	v_mov_b32_e32 v109, v21
	v_mov_b32_e32 v108, v20
	v_mov_b32_e32 v107, v19
	v_mov_b32_e32 v106, v18
	v_mov_b32_e32 v113, v25
	v_mov_b32_e32 v112, v24
	v_mov_b32_e32 v111, v23
	v_mov_b32_e32 v110, v22
	v_mov_b32_e32 v121, v29
	v_mov_b32_e32 v120, v28
	v_mov_b32_e32 v119, v27
	v_mov_b32_e32 v118, v26
	v_mov_b32_e32 v125, v33
	v_mov_b32_e32 v124, v32
	v_mov_b32_e32 v123, v31
	v_mov_b32_e32 v122, v30
	v_mov_b32_e32 v129, v37
	v_mov_b32_e32 v128, v36
	v_mov_b32_e32 v127, v35
	v_mov_b32_e32 v126, v34
	s_branch .LBB0_1228
